# H1b: attention: the 8 V0 transposed reads of the X head hoisted into the end of the preceding Y section (V tile staged two sections earlier), on top of BE1
# speedup vs baseline: 1.0042x; 1.0017x over previous
.LBB0_629:
	v_max_f32_e32 v148, v84, v85
	v_max_f32_e32 v149, v68, v69
	v_max3_f32 v148, v148, v86, v87
	v_max3_f32 v149, v149, v70, v71
	v_max3_f32 v148, v148, v88, v89
	v_max3_f32 v149, v149, v72, v73
	v_max3_f32 v148, v148, v90, v91
	v_max3_f32 v149, v149, v74, v75
	v_max3_f32 v148, v148, v92, v93
	v_max3_f32 v149, v149, v76, v77
	v_max3_f32 v148, v148, v94, v95
	v_max3_f32 v149, v149, v78, v79
	v_max3_f32 v148, v148, v96, v97
	v_max3_f32 v149, v149, v80, v81
	v_max3_f32 v148, v148, v98, v99
	v_max3_f32 v149, v149, v82, v83
	v_max_f32_e32 v148, v148, v149
	v_mov_b32_e32 v149, v148
	s_nop 1
	v_permlane32_swap_b32_e32 v148, v149
	v_max_f32_e32 v148, v148, v149
	v_sub_f32_e32 v149, v148, v182
	v_cmp_ge_f32_e32 vcc, s23, v149
	v_max_f32_e32 v148, v182, v148
	s_cmp_eq_u64 vcc, exec
	s_cselect_b64 vcc, -1, 0
	v_sub_f32_e32 v150, v182, v148
	v_cndmask_b32_e32 v182, v148, v182, vcc
	v_mul_f32_e32 v148, 0xbe0293ee, v182
	v_fmamk_f32 v84, v84, 0x3e0293ee, v148
	v_fmamk_f32 v85, v85, 0x3e0293ee, v148
	v_fmamk_f32 v86, v86, 0x3e0293ee, v148
	v_fmamk_f32 v87, v87, 0x3e0293ee, v148
	v_fmamk_f32 v88, v88, 0x3e0293ee, v148
	v_fmamk_f32 v89, v89, 0x3e0293ee, v148
	v_fmamk_f32 v90, v90, 0x3e0293ee, v148
	v_fmamk_f32 v91, v91, 0x3e0293ee, v148
	v_fmamk_f32 v92, v92, 0x3e0293ee, v148
	v_fmamk_f32 v93, v93, 0x3e0293ee, v148
	v_fmamk_f32 v94, v94, 0x3e0293ee, v148
	v_fmamk_f32 v95, v95, 0x3e0293ee, v148
	v_fmamk_f32 v96, v96, 0x3e0293ee, v148
	v_fmamk_f32 v97, v97, 0x3e0293ee, v148
	v_fmamk_f32 v98, v98, 0x3e0293ee, v148
	v_fmamk_f32 v99, v99, 0x3e0293ee, v148
	v_fmamk_f32 v68, v68, 0x3e0293ee, v148
	v_fmamk_f32 v69, v69, 0x3e0293ee, v148
	v_fmamk_f32 v70, v70, 0x3e0293ee, v148
	v_fmamk_f32 v71, v71, 0x3e0293ee, v148
	v_fmamk_f32 v72, v72, 0x3e0293ee, v148
	v_fmamk_f32 v73, v73, 0x3e0293ee, v148
	v_fmamk_f32 v74, v74, 0x3e0293ee, v148
	v_fmamk_f32 v75, v75, 0x3e0293ee, v148
	v_fmamk_f32 v76, v76, 0x3e0293ee, v148
	v_fmamk_f32 v77, v77, 0x3e0293ee, v148
	v_fmamk_f32 v78, v78, 0x3e0293ee, v148
	v_fmamk_f32 v79, v79, 0x3e0293ee, v148
	v_fmamk_f32 v80, v80, 0x3e0293ee, v148
	v_fmamk_f32 v81, v81, 0x3e0293ee, v148
	v_fmamk_f32 v82, v82, 0x3e0293ee, v148
	v_fmac_f32_e32 v148, 0x3e0293ee, v83
	v_exp_f32_e32 v83, v84
	v_exp_f32_e32 v84, v85
	v_exp_f32_e32 v85, v86
	v_add_f32_e32 v149, v84, v83
	v_exp_f32_e32 v86, v87
	v_add_f32_e32 v149, v85, v149
	v_exp_f32_e32 v87, v88
	v_add_f32_e32 v149, v86, v149
	v_exp_f32_e32 v88, v89
	v_add_f32_e32 v149, v87, v149
	v_exp_f32_e32 v89, v90
	v_add_f32_e32 v149, v88, v149
	v_exp_f32_e32 v90, v91
	v_add_f32_e32 v149, v89, v149
	v_exp_f32_e32 v91, v92
	v_add_f32_e32 v149, v90, v149
	v_exp_f32_e32 v92, v93
	v_add_f32_e32 v149, v91, v149
	v_exp_f32_e32 v93, v94
	v_add_f32_e32 v149, v92, v149
	v_exp_f32_e32 v94, v95
	v_add_f32_e32 v149, v93, v149
	v_exp_f32_e32 v95, v96
	v_add_f32_e32 v149, v94, v149
	v_exp_f32_e32 v96, v97
	v_add_f32_e32 v149, v95, v149
	v_exp_f32_e32 v97, v98
	v_add_f32_e32 v149, v96, v149
	v_exp_f32_e32 v98, v99
	v_add_f32_e32 v149, v97, v149
	v_exp_f32_e32 v99, v148
	v_add_f32_e32 v149, v98, v149
	v_exp_f32_e32 v68, v68
	v_exp_f32_e32 v69, v69
	v_add_f32_e32 v149, v68, v149
	v_exp_f32_e32 v70, v70
	v_add_f32_e32 v149, v69, v149
	v_exp_f32_e32 v71, v71
	v_add_f32_e32 v149, v70, v149
	v_exp_f32_e32 v72, v72
	v_add_f32_e32 v149, v71, v149
	v_exp_f32_e32 v73, v73
	v_add_f32_e32 v149, v72, v149
	v_exp_f32_e32 v74, v74
	v_add_f32_e32 v149, v73, v149
	v_exp_f32_e32 v75, v75
	v_add_f32_e32 v149, v74, v149
	v_exp_f32_e32 v76, v76
	v_add_f32_e32 v149, v75, v149
	v_exp_f32_e32 v77, v77
	v_add_f32_e32 v149, v76, v149
	v_exp_f32_e32 v78, v78
	v_add_f32_e32 v149, v77, v149
	v_exp_f32_e32 v79, v79
	v_add_f32_e32 v149, v78, v149
	v_exp_f32_e32 v80, v80
	v_add_f32_e32 v149, v79, v149
	v_exp_f32_e32 v81, v81
	v_add_f32_e32 v149, v80, v149
	v_exp_f32_e32 v82, v82
	v_add_f32_e32 v149, v81, v149
	v_mul_f32_e32 v150, 0x3e0293ee, v150
	v_add_f32_e32 v149, v82, v149
	v_exp_f32_e32 v150, v150
	v_add_f32_e32 v185, v99, v149
	v_cndmask_b32_e64 v184, v150, 1.0, vcc
	v_cvt_pk_bf16_f32 v148, v83, v84
	v_cvt_pk_bf16_f32 v149, v85, v86
	v_cvt_pk_bf16_f32 v150, v87, v88
	v_cvt_pk_bf16_f32 v151, v89, v90
	v_cvt_pk_bf16_f32 v152, v91, v92
	v_cvt_pk_bf16_f32 v153, v93, v94
	v_cvt_pk_bf16_f32 v154, v95, v96
	v_cvt_pk_bf16_f32 v155, v97, v98
	v_cvt_pk_bf16_f32 v156, v68, v69
	v_cvt_pk_bf16_f32 v157, v70, v71
	v_cvt_pk_bf16_f32 v158, v72, v73
	v_cvt_pk_bf16_f32 v159, v74, v75
	v_cvt_pk_bf16_f32 v160, v76, v77
	v_cvt_pk_bf16_f32 v161, v78, v79
	v_cvt_pk_bf16_f32 v162, v80, v81
	v_cvt_pk_bf16_f32 v163, v82, v99
	s_mov_b32 s53, s52
	v_lshl_add_u32 v187, s53, 14, v173
	ds_read_b64_tr_b16 v[188:189], v187 offset:0
	ds_read_b64_tr_b16 v[190:191], v187 offset:0x800
	ds_read_b64_tr_b16 v[192:193], v187 offset:0x1000
	ds_read_b64_tr_b16 v[194:195], v187 offset:0x1800
	ds_read_b64_tr_b16 v[196:197], v187 offset:0x2000
	ds_read_b64_tr_b16 v[198:199], v187 offset:0x2800
	ds_read_b64_tr_b16 v[200:201], v187 offset:0x3000
	ds_read_b64_tr_b16 v[202:203], v187 offset:0x3800
	s_cbranch_vccnz .LBB0_633
	s_and_saveexec_b64 s[16:17], s[38:39]
	ds_write_b32 v172, v184 offset:128
	s_or_b64 exec, exec, s[16:17]
	s_waitcnt lgkmcnt(0)
	v_add_u32_e32 v80, v171, v168
	ds_read_b128 v[68:71], v80 offset:224
	ds_read_b128 v[72:75], v80 offset:192
	ds_read_b128 v[76:79], v80 offset:160
	ds_read_b128 v[80:83], v80 offset:128
	s_waitcnt lgkmcnt(3)
	v_pk_mul_f32 v[16:17], v[16:17], v[68:69]
	s_waitcnt lgkmcnt(2)
	v_pk_mul_f32 v[12:13], v[12:13], v[72:73]
	s_waitcnt lgkmcnt(1)
	v_pk_mul_f32 v[8:9], v[8:9], v[76:77]
	v_pk_mul_f32 v[18:19], v[18:19], v[70:71]
	v_pk_mul_f32 v[14:15], v[14:15], v[74:75]
	v_pk_mul_f32 v[10:11], v[10:11], v[78:79]
	s_waitcnt lgkmcnt(0)
	v_pk_mul_f32 v[6:7], v[6:7], v[82:83]
	v_pk_mul_f32 v[4:5], v[4:5], v[80:81]
	v_pk_mul_f32 v[64:65], v[64:65], v[68:69]
	v_pk_mul_f32 v[60:61], v[60:61], v[72:73]
	v_pk_mul_f32 v[56:57], v[56:57], v[76:77]
	v_pk_mul_f32 v[66:67], v[66:67], v[70:71]
	v_pk_mul_f32 v[62:63], v[62:63], v[74:75]
	v_pk_mul_f32 v[58:59], v[58:59], v[78:79]
	v_pk_mul_f32 v[54:55], v[54:55], v[82:83]
	v_pk_mul_f32 v[52:53], v[52:53], v[80:81]
	v_pk_mul_f32 v[48:49], v[48:49], v[68:69]
	v_pk_mul_f32 v[44:45], v[44:45], v[72:73]
	v_pk_mul_f32 v[40:41], v[40:41], v[76:77]
	v_pk_mul_f32 v[50:51], v[50:51], v[70:71]
	v_pk_mul_f32 v[46:47], v[46:47], v[74:75]
	v_pk_mul_f32 v[42:43], v[42:43], v[78:79]
	v_pk_mul_f32 v[38:39], v[38:39], v[82:83]
	v_pk_mul_f32 v[36:37], v[36:37], v[80:81]
	v_pk_mul_f32 v[32:33], v[32:33], v[68:69]
	v_pk_mul_f32 v[28:29], v[28:29], v[72:73]
	v_pk_mul_f32 v[24:25], v[24:25], v[76:77]
	v_pk_mul_f32 v[34:35], v[34:35], v[70:71]
	v_pk_mul_f32 v[30:31], v[30:31], v[74:75]
	v_pk_mul_f32 v[26:27], v[26:27], v[78:79]
	v_pk_mul_f32 v[22:23], v[22:23], v[82:83]
	v_pk_mul_f32 v[20:21], v[20:21], v[80:81]
.LBB0_633:
	s_barrier
	s_lshl_b32 s52, s49, 14
	v_add_u32_e32 v208, s52, v174
	ds_read_b128 v[68:71], v208 offset:0
	ds_read_b128 v[72:75], v208 offset:0x2000
	v_add_u32_e32 v209, s52, v175
	ds_read_b128 v[204:207], v209 offset:0
	ds_read_b128 v[216:219], v209 offset:0x2000
	v_add_u32_e32 v210, s52, v176
	ds_read_b128 v[220:223], v210 offset:0
	ds_read_b128 v[224:227], v210 offset:0x2000
	v_add_u32_e32 v211, s52, v177
	ds_read_b128 v[228:231], v211 offset:0
	ds_read_b128 v[232:235], v211 offset:0x2000
	s_waitcnt lgkmcnt(4)
	v_mfma_f32_32x32x16_bf16 v[84:99], v[68:71], v[128:131], 0
	v_mfma_f32_32x32x16_bf16 v[68:83], v[72:75], v[128:131], 0
	v_mfma_f32_32x32x16_bf16 v[84:99], v[204:207], v[124:127], v[84:99]
	v_mfma_f32_32x32x16_bf16 v[68:83], v[216:219], v[124:127], v[68:83]
	ds_read_b128 v[204:207], v208 offset:0x80
	ds_read_b128 v[216:219], v208 offset:0x2080
	ds_read_b128 v[236:239], v209 offset:0x80
	ds_read_b128 v[242:245], v209 offset:0x2080
	s_waitcnt lgkmcnt(4)
	v_mfma_f32_32x32x16_bf16 v[84:99], v[220:223], v[120:123], v[84:99]
	v_mfma_f32_32x32x16_bf16 v[68:83], v[224:227], v[120:123], v[68:83]
	v_mfma_f32_32x32x16_bf16 v[84:99], v[228:231], v[116:119], v[84:99]
	v_mfma_f32_32x32x16_bf16 v[68:83], v[232:235], v[116:119], v[68:83]
	ds_read_b128 v[220:223], v210 offset:0x80
	ds_read_b128 v[224:227], v210 offset:0x2080
	ds_read_b128 v[228:231], v211 offset:0x80
	ds_read_b128 v[232:235], v211 offset:0x2080
	s_waitcnt lgkmcnt(4)
	v_mfma_f32_32x32x16_bf16 v[84:99], v[204:207], v[112:115], v[84:99]
	v_mfma_f32_32x32x16_bf16 v[68:83], v[216:219], v[112:115], v[68:83]
	v_mfma_f32_32x32x16_bf16 v[84:99], v[236:239], v[108:111], v[84:99]
	v_mfma_f32_32x32x16_bf16 v[68:83], v[242:245], v[108:111], v[68:83]
	s_waitcnt lgkmcnt(0)
	v_mfma_f32_32x32x16_bf16 v[84:99], v[220:223], v[104:107], v[84:99]
	v_mfma_f32_32x32x16_bf16 v[68:83], v[224:227], v[104:107], v[68:83]
	v_mfma_f32_32x32x16_bf16 v[84:99], v[228:231], v[100:103], v[84:99]
	v_mfma_f32_32x32x16_bf16 v[68:83], v[232:235], v[100:103], v[68:83]
	ds_read_b64_tr_b16 v[204:205], v187 offset:0x200
	ds_read_b64_tr_b16 v[206:207], v187 offset:0xa00
	ds_read_b64_tr_b16 v[216:217], v187 offset:0x1200
	ds_read_b64_tr_b16 v[218:219], v187 offset:0x1a00
	ds_read_b64_tr_b16 v[220:221], v187 offset:0x2200
	ds_read_b64_tr_b16 v[222:223], v187 offset:0x2a00
	ds_read_b64_tr_b16 v[224:225], v187 offset:0x3200
	ds_read_b64_tr_b16 v[226:227], v187 offset:0x3a00
	s_waitcnt lgkmcnt(8)
	v_mfma_f32_32x32x16_bf16 v[4:19], v[148:151], v[188:191], v[4:19]
	s_lshl_b32 s19, s51, 14
	s_add_i32 s8, s19, 0
	v_add_u32_e32 v236, s8, v179
	s_waitcnt vmcnt(0)
	v_mfma_f32_32x32x16_bf16 v[4:19], v[152:155], v[192:195], v[4:19]
	ds_write_b128 v236, v[144:147]
	v_add_u32_e32 v236, s8, v178
	v_mfma_f32_32x32x16_bf16 v[4:19], v[156:159], v[196:199], v[4:19]
	ds_write_b128 v236, v[136:139]
	v_add_u32_e32 v236, s8, v180
	v_mfma_f32_32x32x16_bf16 v[4:19], v[160:163], v[200:203], v[4:19]
	ds_read_b64_tr_b16 v[188:189], v187 offset:0x400
	ds_read_b64_tr_b16 v[190:191], v187 offset:0xc00
	ds_read_b64_tr_b16 v[192:193], v187 offset:0x1400
	ds_read_b64_tr_b16 v[194:195], v187 offset:0x1c00
	ds_read_b64_tr_b16 v[196:197], v187 offset:0x2400
	ds_read_b64_tr_b16 v[198:199], v187 offset:0x2c00
	ds_read_b64_tr_b16 v[200:201], v187 offset:0x3400
	ds_read_b64_tr_b16 v[202:203], v187 offset:0x3c00
	s_waitcnt lgkmcnt(10)
	v_mfma_f32_32x32x16_bf16 v[52:67], v[148:151], v[204:207], v[52:67]
	ds_write_b128 v236, v[140:143] offset:49152
	v_add_u32_e32 v236, s8, v181
	v_mfma_f32_32x32x16_bf16 v[52:67], v[152:155], v[216:219], v[52:67]
	ds_write_b128 v236, v[132:135] offset:49152
	s_add_i32 s48, s48, 1
	v_mfma_f32_32x32x16_bf16 v[52:67], v[156:159], v[220:223], v[52:67]
	s_sub_i32 s8, s50, s47
	s_min_u32 s36, s50, s8
	s_lshl_b64 s[8:9], s[36:37], 10
	s_cmp_lt_u32 s50, s47
	s_cselect_b32 s16, s30, s20
	s_cselect_b32 s17, s31, s21
	v_mfma_f32_32x32x16_bf16 v[52:67], v[160:163], v[224:227], v[52:67]
	ds_read_b64_tr_b16 v[204:205], v187 offset:0x600
	ds_read_b64_tr_b16 v[206:207], v187 offset:0xe00
	ds_read_b64_tr_b16 v[216:217], v187 offset:0x1600
	ds_read_b64_tr_b16 v[218:219], v187 offset:0x1e00
	ds_read_b64_tr_b16 v[220:221], v187 offset:0x2600
	ds_read_b64_tr_b16 v[222:223], v187 offset:0x2e00
	ds_read_b64_tr_b16 v[224:225], v187 offset:0x3600
	ds_read_b64_tr_b16 v[226:227], v187 offset:0x3e00
	s_waitcnt lgkmcnt(10)
	v_mfma_f32_32x32x16_bf16 v[36:51], v[148:151], v[188:191], v[36:51]
	s_cselect_b32 s36, s42, s26
	s_cselect_b32 s54, s43, s27
	s_add_u32 s16, s16, s8
	s_addc_u32 s17, s17, s9
	s_add_u32 s8, s36, s8
	s_addc_u32 s9, s54, s9
	v_mfma_f32_32x32x16_bf16 v[36:51], v[152:155], v[192:195], v[36:51]
	global_load_dwordx4 v[144:147], v2, s[8:9]
	s_add_u32 s8, s8, 0x8000
	s_addc_u32 s9, s9, 0
	v_mfma_f32_32x32x16_bf16 v[36:51], v[156:159], v[196:199], v[36:51]
	global_load_dwordx4 v[136:139], v2, s[8:9]
	global_load_dwordx4 v[140:143], v2, s[16:17]
	v_mfma_f32_32x32x16_bf16 v[36:51], v[160:163], v[200:203], v[36:51]
	s_add_u32 s16, s16, 0x8000
	s_addc_u32 s17, s17, 0
	global_load_dwordx4 v[132:135], v2, s[16:17]
	s_waitcnt lgkmcnt(0)
	v_mfma_f32_32x32x16_bf16 v[20:35], v[148:151], v[204:207], v[20:35]
	v_mfma_f32_32x32x16_bf16 v[20:35], v[152:155], v[216:219], v[20:35]
	v_mfma_f32_32x32x16_bf16 v[20:35], v[156:159], v[220:223], v[20:35]
	v_mfma_f32_32x32x16_bf16 v[20:35], v[160:163], v[224:227], v[20:35]
